# attention tile tail: the two 16-term row-sum chains interleaved instead of one 32-term chain
# baseline (speedup 1.0000x reference)
.Lcj_cx_0:
	v_add_f32_e32 v96, v135, v96
	v_add_f32_e32 v80, v81, v80
	v_add_f32_e32 v96, v97, v96
	v_add_f32_e32 v80, v82, v80
	v_add_f32_e32 v96, v98, v96
	v_add_f32_e32 v80, v83, v80
	v_add_f32_e32 v96, v99, v96
	v_add_f32_e32 v80, v84, v80
	v_add_f32_e32 v96, v100, v96
	v_add_f32_e32 v80, v85, v80
	v_add_f32_e32 v96, v101, v96
	v_add_f32_e32 v80, v86, v80
	v_add_f32_e32 v96, v102, v96
	v_add_f32_e32 v80, v87, v80
	v_add_f32_e32 v96, v103, v96
	v_add_f32_e32 v80, v88, v80
	v_add_f32_e32 v96, v104, v96
	v_add_f32_e32 v80, v89, v80
	v_add_f32_e32 v96, v105, v96
	v_add_f32_e32 v80, v90, v80
	v_add_f32_e32 v96, v106, v96
	v_add_f32_e32 v80, v91, v80
	v_add_f32_e32 v96, v107, v96
	v_add_f32_e32 v80, v92, v80
	v_add_f32_e32 v96, v108, v96
	v_add_f32_e32 v80, v93, v80
	v_add_f32_e32 v96, v109, v96
	v_add_f32_e32 v80, v94, v80
	v_add_f32_e32 v96, v110, v96
	v_add_f32_e32 v80, v95, v80
	v_add_f32_e32 v96, v111, v96
	v_add_f32_e32 v135, v80, v96
	s_branch .Lcj_common_0
.Lcj_c5_0:
	v_add_f32_e32 v96, v135, v96
	s_waitcnt vmcnt(6)
	v_cvt_pk_bf16_f32 v224, v224, v228
	v_add_f32_e32 v80, v81, v80
	v_cvt_pk_bf16_f32 v228, v225, v229
	v_cvt_pk_bf16_f32 v225, v232, v236
	v_add_f32_e32 v96, v97, v96
	v_cvt_pk_bf16_f32 v232, v226, v230
	v_cvt_pk_bf16_f32 v226, v240, v244
	v_add_f32_e32 v80, v82, v80
	v_cvt_pk_bf16_f32 v236, v227, v231
	v_cvt_pk_bf16_f32 v227, v248, v252
	v_add_f32_e32 v96, v98, v96
	v_cvt_pk_bf16_f32 v229, v233, v237
	v_cvt_pk_bf16_f32 v230, v241, v245
	v_add_f32_e32 v80, v83, v80
	v_cvt_pk_bf16_f32 v231, v249, v253
	v_cvt_pk_bf16_f32 v233, v234, v238
	v_add_f32_e32 v96, v99, v96
	v_cvt_pk_bf16_f32 v234, v242, v246
	v_cvt_pk_bf16_f32 v237, v235, v239
	v_add_f32_e32 v80, v84, v80
	v_cvt_pk_bf16_f32 v235, v250, v254
	v_cvt_pk_bf16_f32 v238, v243, v247
	v_add_f32_e32 v96, v100, v96
	v_cvt_pk_bf16_f32 v239, v251, v255
	s_lshr_b32 s91, s2, 7
	v_add_f32_e32 v80, v85, v80
	s_lshl_b32 s92, s98, 1
	s_add_i32 s91, s91, s92
	v_add_f32_e32 v96, v101, v96
	s_mul_i32 s92, s91, 0xab
	s_lshr_b32 s92, s92, 9
	v_add_f32_e32 v80, v86, v80
	s_mul_i32 s93, s92, 3
	s_sub_i32 s91, s91, s93
	v_add_f32_e32 v96, v102, v96
	v_mbcnt_lo_u32_b32 v222, -1, 0
	v_mbcnt_hi_u32_b32 v222, -1, v222
	v_add_f32_e32 v80, v87, v80
	s_and_b32 s93, s2, 0x7f
	s_lshl_b32 s93, s93, 9
	v_add_f32_e32 v96, v103, v96
	s_or_b32 s93, s93, s63
	v_or_b32_e32 v222, s93, v222
	v_add_f32_e32 v80, v88, v80
	s_cmp_eq_u32 s91, 2
	s_cselect_b32 s93, 12, 11
	v_add_f32_e32 v96, v104, v96
	v_lshrrev_b32_e32 v223, s93, v222
	v_and_b32_e32 v208, 7, v222
	v_add_f32_e32 v80, v89, v80
	v_lshl_or_b32 v223, v223, 3, v208
	s_cselect_b32 s93, 6, 5
	v_add_f32_e32 v96, v105, v96
	v_bfe_u32 v208, v222, 6, s93
	v_lshrrev_b32_e32 v222, 1, v222
	v_add_f32_e32 v80, v90, v80
	v_and_b32_e32 v222, 28, v222
	v_lshl_or_b32 v222, v208, 5, v222
	v_add_f32_e32 v96, v106, v96
	s_cselect_b64 vcc, exec, 0
	s_cselect_b32 s94, 11, 12
	v_add_f32_e32 v80, v91, v80
	s_cselect_b64 s[100:101], s[86:87], s[84:85]
	s_cselect_b32 s93, 22, 23
	v_add_f32_e32 v96, v107, v96
	v_lshrrev_b32_e32 v208, 7, v222
	v_and_b32_e32 v240, 0x7f, v222
	v_add_f32_e32 v80, v92, v80
	s_lshl_b32 s92, s92, s93
	v_lshl_or_b32 v208, v208, 8, v240
	v_add_f32_e32 v96, v108, v96
	s_lshl_b32 s93, s91, 7
	v_or_b32_e32 v208, s93, v208
	v_add_f32_e32 v80, v93, v80
	v_cndmask_b32_e32 v222, v208, v222, vcc
	v_lshlrev_b32_e32 v222, s94, v222
	v_add_f32_e32 v96, v109, v96
	s_lshl_b32 s94, 1, s94
	v_lshl_or_b32 v222, v223, 4, v222
	v_add_f32_e32 v80, v94, v80
	s_add_u32 s100, s100, s92
	s_addc_u32 s101, s101, 0
	v_add_f32_e32 v96, v110, v96
	s_mov_b32 s95, 5
	v_add_f32_e32 v80, v95, v80
	v_add_f32_e32 v96, v111, v96
	v_add_f32_e32 v135, v80, v96
	s_branch .Lcj_common_0
.Lcj_c7_0:
	v_add_f32_e32 v96, v135, v96
	s_add_i32 s98, s98, 1
	s_min_u32 s98, s98, 47
	v_add_f32_e32 v80, v81, v80
	s_lshr_b32 s91, s2, 7
	s_lshl_b32 s92, s98, 1
	v_add_f32_e32 v96, v97, v96
	s_add_i32 s91, s91, s92
	s_mul_i32 s92, s91, 0xab
	v_add_f32_e32 v80, v82, v80
	s_lshr_b32 s92, s92, 9
	s_mul_i32 s93, s92, 3
	v_add_f32_e32 v96, v98, v96
	s_sub_i32 s91, s91, s93
	v_mbcnt_lo_u32_b32 v222, -1, 0
	v_add_f32_e32 v80, v83, v80
	v_mbcnt_hi_u32_b32 v222, -1, v222
	s_and_b32 s93, s2, 0x7f
	v_add_f32_e32 v96, v99, v96
	s_lshl_b32 s93, s93, 9
	s_or_b32 s93, s93, s63
	v_add_f32_e32 v80, v84, v80
	v_or_b32_e32 v222, s93, v222
	s_cmp_eq_u32 s91, 2
	v_add_f32_e32 v96, v100, v96
	s_cselect_b32 s93, 12, 11
	v_lshrrev_b32_e32 v223, s93, v222
	v_add_f32_e32 v80, v85, v80
	v_and_b32_e32 v208, 7, v222
	v_lshl_or_b32 v223, v223, 3, v208
	v_add_f32_e32 v96, v101, v96
	s_cselect_b32 s93, 6, 5
	v_bfe_u32 v208, v222, 6, s93
	v_add_f32_e32 v80, v86, v80
	v_lshrrev_b32_e32 v222, 1, v222
	v_and_b32_e32 v222, 28, v222
	v_add_f32_e32 v96, v102, v96
	v_lshl_or_b32 v222, v208, 5, v222
	v_lshlrev_b32_e32 v222, 2, v222
	v_add_f32_e32 v80, v87, v80
	s_cselect_b32 s93, 16, 15
	v_lshlrev_b32_e32 v223, s93, v223
	v_add_f32_e32 v96, v103, v96
	v_add_u32_e32 v222, v223, v222
	s_cselect_b32 s94, 1, 0
	v_add_f32_e32 v80, v88, v80
	s_lshl_b32 s94, 0x1000, s94
	s_lshl_b32 s92, s92, 23
	v_add_f32_e32 v96, v104, v96
	s_cmp_eq_u32 s91, 0
	s_cselect_b64 s[100:101], s[76:77], s[78:79]
	v_add_f32_e32 v80, v89, v80
	s_cmp_eq_u32 s91, 2
	s_cselect_b64 s[100:101], s[80:81], s[100:101]
	v_add_f32_e32 v96, v105, v96
	s_add_u32 s100, s100, s92
	s_addc_u32 s101, s101, 0
	v_add_f32_e32 v80, v90, v80
	s_mov_b32 s95, 1
	s_cmp_lt_u32 s4, 56
	v_add_f32_e32 v96, v106, v96
	s_cselect_b32 s95, 1, 0
	v_add_f32_e32 v80, v91, v80
	v_add_f32_e32 v96, v107, v96
	v_add_f32_e32 v80, v92, v80
	v_add_f32_e32 v96, v108, v96
	v_add_f32_e32 v80, v93, v80
	v_add_f32_e32 v96, v109, v96
	v_add_f32_e32 v80, v94, v80
	v_add_f32_e32 v96, v110, v96
	v_add_f32_e32 v80, v95, v80
	v_add_f32_e32 v96, v111, v96
	v_add_f32_e32 v135, v80, v96
